# attention: V-fragment address 2 VALU/tile, no vmcnt(0) before first QK of a unit; P6: both previous-row loads in flight; on top of v5
# baseline (speedup 1.0000x reference)
; #define ATT_ISSUE_K(jt, stage) do { _Pragma("unroll") for (int i_ = 0; i_ < 3; ++i_) ATT_DMA(kg + (size_t)(jt) * KTILE + kgo[i_], KRING + (stage) * KTILE + (wave * 3 + i_) * 1024); } while (0)
; #define ATT_ISSUE_V(jt, stage) do { _Pragma("unroll") for (int i_ = 0; i_ < 2; ++i_) ATT_DMA(vg + (size_t)(jt) * 128 + vgo[i_], VRING + (stage) * VTILE + (wave * 2 + i_) * 1024); } while (0)
; __device__ __forceinline__ void attn_unit(LAS unsigned char* lds, const bf16_t* Qg, const bf16_t* Kg, const bf16_t* Vtg, bf16_t* Og, int bh, int qb, int tid_, int wave, int lane_) {
;     ...
;     { const bf16_t* qp = Qg + ((size_t)bh * SEQ + 128 * qb + 32 * rg + r) * QKD + 8 * hi;
; #pragma unroll
;       for (int kk = 0; kk < 12; ++kk) qf[kk] = *(const bf16x8*)(qp + 16 * kk); }
;     const unsigned char* kg = (const unsigned char*)(Kg + (size_t)bh * SEQ * QKD);
;     const unsigned char* vg = (const unsigned char*)(Vtg + (size_t)bh * VD * SEQ);
;     unsigned kgo[3], vgo[2];
; #pragma unroll
;     for (int i = 0; i < 3; ++i) { const int a = (wave * 3 + i) * 1024 + lane * 16, row = a / 384, cp = (a % 384) >> 4, cl = (cp & ~7) | ((cp ^ (row >> 1)) & 7); kgo[i] = (unsigned)(row * 384 + cl * 16); }
; #pragma unroll
;     for (int i = 0; i < 2; ++i) { const int a = (wave * 2 + i) * 1024 + lane * 16, row = a >> 7, cp = (a & 127) >> 4, cl = (cp ^ (row >> 1)) & 7; vgo[i] = (unsigned)(row * (SEQ * 2) + cl * 16); }
;     const int sw = (r >> 1) & 7;
;     unsigned kro[4], vro[2];
; #pragma unroll
;     for (int q = 0; q < 4; ++q) kro[q] = (unsigned)((32 * kh + r) * 384 + (((2 * q + hi) ^ sw) * 16));
; #pragma unroll
;     for (int s = 0; s < 2; ++s) vro[s] = (unsigned)(VRING + r * 128 + (((4 * kh + 2 * s + hi) ^ sw) * 16));
;     f32x16 o[4]; float mrun = NEG, lrun = 0.f;
; #pragma unroll
;     for (int dt = 0; dt < 4; ++dt)
; #pragma unroll
;         for (int i = 0; i < 16; ++i) o[dt][i] = 0.f;
;     ATT_ISSUE_K(0, 0); ATT_ISSUE_V(0, 0); ATT_ISSUE_K(1, 1);
;     ATT_ISSUE_K((2 < nt) ? 2 : nt - 1, 2); ATT_ISSUE_V(1, 1);
;     asm volatile("s_waitcnt vmcnt(5)" ::: "memory"); __builtin_amdgcn_s_barrier(); asm volatile("" ::: "memory");
.LBB0_475:
	s_ashr_i32 s40, s72, 3
	s_sub_i32 s0, 63, s40
	s_and_b32 s73, s72, 7
	s_lshl_b32 s66, s0, 7
	s_mov_b64 s[8:9], s[88:89]
	s_lshl_b32 s44, s0, 1
	s_lshl_b32 s41, s73, 13
	s_ashr_i32 s88, s66, 31
	v_mov_b32_e32 v4, v254
	s_add_u32 s0, s41, s66
	s_addc_u32 s4, 0, s88
	v_and_b32_e32 v180, 31, v4
	s_or_b32 s0, s0, s97
	v_or_b32_e32 v0, s0, v180
	v_bfe_u32 v24, v4, 5, 1
	v_mad_u64_u32 v[0:1], s[0:1], v0, s61, v[178:179]
	v_mad_i32_i24 v1, s4, v195, v1
	v_lshlrev_b32_e32 v176, 4, v24
	v_and_b32_e32 v181, 63, v4
	v_lshl_add_u64 v[0:1], v[0:1], 0, v[176:177]
	global_load_dwordx4 v[96:99], v[0:1], off
	global_load_dwordx4 v[100:103], v[0:1], off offset:32
	global_load_dwordx4 v[104:107], v[0:1], off offset:64
	global_load_dwordx4 v[108:111], v[0:1], off offset:96
	global_load_dwordx4 v[112:115], v[0:1], off offset:128
	global_load_dwordx4 v[116:119], v[0:1], off offset:160
	global_load_dwordx4 v[120:123], v[0:1], off offset:192
	global_load_dwordx4 v[124:127], v[0:1], off offset:224
	global_load_dwordx4 v[128:131], v[0:1], off offset:256
	global_load_dwordx4 v[132:135], v[0:1], off offset:288
	global_load_dwordx4 v[136:139], v[0:1], off offset:320
	global_load_dwordx4 v[140:143], v[0:1], off offset:352
	v_lshlrev_b32_e32 v0, 4, v181
	v_or_b32_e32 v1, s59, v0
	v_mul_hi_i32 v2, v1, s42
	v_lshrrev_b32_e32 v3, 31, v2
	v_ashrrev_i32_e32 v2, 6, v2
	v_add_u32_e32 v2, v2, v3
	v_mul_i32_i24_e32 v3, 0x180, v2
	v_lshlrev_b32_e32 v2, 3, v2
	v_sub_u32_e32 v1, v1, v3
	v_and_b32_e32 v2, 0x70, v2
	v_xad_u32 v176, v2, v1, v3
	v_or_b32_e32 v1, s60, v0
	v_mul_hi_i32 v2, v1, s42
	v_lshrrev_b32_e32 v3, 31, v2
	v_ashrrev_i32_e32 v2, 6, v2
	v_add_u32_e32 v2, v2, v3
	v_mul_i32_i24_e32 v3, 0x180, v2
	v_lshlrev_b32_e32 v2, 3, v2
	v_sub_u32_e32 v1, v1, v3
	v_and_b32_e32 v2, 0x70, v2
	v_xad_u32 v182, v2, v1, v3
	v_or_b32_e32 v1, s67, v0
	v_mul_hi_i32 v2, v1, s42
	v_lshrrev_b32_e32 v3, 31, v2
	v_ashrrev_i32_e32 v2, 6, v2
	v_add_u32_e32 v2, v2, v3
	v_mul_i32_i24_e32 v3, 0x180, v2
	v_lshlrev_b32_e32 v2, 3, v2
	s_mul_i32 s0, s73, 0x300000
	s_lshl_b32 s1, s73, 21
	v_sub_u32_e32 v1, v1, v3
	v_and_b32_e32 v2, 0x70, v2
	v_readlane_b32 s4, v255, 32
	v_xad_u32 v184, v2, v1, v3
	v_readlane_b32 s5, v255, 33
	s_add_u32 s92, s4, s0
	v_or_b32_e32 v0, s68, v0
	v_lshlrev_b32_e32 v2, 4, v4
	v_and_b32_e32 v3, 48, v4
	s_mov_b32 m0, s71
	s_addc_u32 s93, s5, 0
	v_lshlrev_b32_e32 v1, 7, v0
	v_bitop3_b32 v2, v2, v3, s86 bitop3:0x6c
	v_or_b32_e32 v0, 0x400, v0
	v_and_or_b32 v186, v1, s62, v2
	v_lshrrev_b32_e32 v1, 8, v0
	s_add_i32 s89, s44, 2
	global_load_lds_dwordx4 v176, s[92:93]
	s_mov_b32 m0, s91
	v_readlane_b32 s0, v255, 52
	v_xor_b32_e32 v1, v1, v4
	v_lshlrev_b32_e32 v0, 7, v0
	global_load_lds_dwordx4 v182, s[92:93]
	s_mov_b32 m0, s74
	s_add_u32 s94, s0, s1
	v_readlane_b32 s0, v255, 53
	v_and_b32_e32 v0, 0xffffc000, v0
	v_lshlrev_b32_e32 v1, 4, v1
	global_load_lds_dwordx4 v184, s[92:93]
	s_addc_u32 s95, s0, 0
	s_mov_b32 m0, s96
	v_and_or_b32 v188, v1, s86, v0
	global_load_lds_dwordx4 v186, s[94:95]
	s_mov_b32 m0, s43
	s_add_u32 s38, s92, 0x6000
	global_load_lds_dwordx4 v188, s[94:95]
	s_addc_u32 s39, s93, 0
	s_mov_b32 m0, s75
	s_or_b32 s45, s44, 1
	global_load_lds_dwordx4 v176, s[38:39]
	s_mov_b32 m0, s90
	s_add_u32 s0, s92, 0xc000
	global_load_lds_dwordx4 v182, s[38:39]
	s_mov_b32 m0, s2
	s_addc_u32 s1, s93, 0
	global_load_lds_dwordx4 v184, s[38:39]
	s_mov_b32 m0, s85
	v_mov_b32_e32 v187, v177
	global_load_lds_dwordx4 v176, s[0:1]
	s_mov_b32 m0, s87
	v_lshl_add_u64 v[0:1], s[94:95], 0, v[186:187]
	v_mov_b32_e32 v189, v177
	global_load_lds_dwordx4 v182, s[0:1]
	s_mov_b32 m0, s3
	v_lshl_add_u64 v[2:3], s[94:95], 0, v[188:189]
	global_load_lds_dwordx4 v184, s[0:1]
	v_lshl_add_u64 v[0:1], v[0:1], 0, s[78:79]
	s_mov_b32 m0, s33
	v_or_b32_e32 v5, s70, v24
	global_load_lds_dwordx4 v[0:1], off
	v_lshl_add_u64 v[0:1], v[2:3], 0, s[78:79]
	s_mov_b32 m0, s10
	s_mov_b32 s48, s49
	global_load_lds_dwordx4 v[0:1], off
	v_lshrrev_b32_e32 v0, 1, v4
	v_or_b32_e32 v1, s69, v180
	v_bfe_u32 v4, v4, 1, 3
	v_mul_lo_u32 v1, v1, s61
	v_bitop3_b32 v0, v24, v0, 7 bitop3:0x78
	v_lshl_or_b32 v191, v0, 4, v1
	v_bitop3_b32 v0, v24, v4, 2 bitop3:0x36
	v_lshl_or_b32 v197, v0, 4, v1
	v_bitop3_b32 v0, v24, v4, 4 bitop3:0x36
	v_lshl_or_b32 v199, v0, 4, v1
	v_bitop3_b32 v0, v24, v4, 6 bitop3:0x36
	s_waitcnt vmcnt(5)
	s_barrier
; #define LAS __attribute__((address_space(3)))
; #define MFMA32(a, b, c) __builtin_amdgcn_mfma_f32_32x32x16_bf16((a), (b), (c), 0, 0, 0)
; #define ATT_ISSUE_K(jt, stage) do { _Pragma("unroll") for (int i_ = 0; i_ < 3; ++i_) ATT_DMA(kg + (size_t)(jt) * KTILE + kgo[i_], KRING + (stage) * KTILE + (wave * 3 + i_) * 1024); } while (0)
; #define ATT_ISSUE_V(jt, stage) do { _Pragma("unroll") for (int i_ = 0; i_ < 2; ++i_) ATT_DMA(vg + (size_t)(jt) * 128 + vgo[i_], VRING + (stage) * VTILE + (wave * 2 + i_) * 1024); } while (0)
; __device__ __forceinline__ void attn_unit(LAS unsigned char* lds, const bf16_t* Qg, const bf16_t* Kg, const bf16_t* Vtg, bf16_t* Og, int bh, int qb, int tid_, int wave, int lane_) {
;     ...
;     for (int s = 0; s < 2; ++s) vro[s] = (unsigned)(VRING + r * 128 + (((4 * kh + 2 * s + hi) ^ sw) * 16));
;     f32x16 o[4]; float mrun = NEG, lrun = 0.f;
; #pragma unroll
;     for (int dt = 0; dt < 4; ++dt)
; #pragma unroll
;         for (int i = 0; i < 16; ++i) o[dt][i] = 0.f;
;     ATT_ISSUE_K(0, 0); ATT_ISSUE_V(0, 0); ATT_ISSUE_K(1, 1);
;     ATT_ISSUE_K((2 < nt) ? 2 : nt - 1, 2); ATT_ISSUE_V(1, 1);
;     asm volatile("s_waitcnt vmcnt(5)" ::: "memory"); __builtin_amdgcn_s_barrier(); asm volatile("" ::: "memory");
;     f32x16 sc, sn;
;     {
; #pragma unroll
;       for (int i = 0; i < 16; ++i) sc[i] = 0.f;
; #pragma unroll
;       for (int kk = 0; kk < 12; ++kk) { const bf16x8 kf = *(const LAS bf16x8*)(lds + KRING + kro[kk & 3] + (kk >> 2) * 128); sc = MFMA32(kf, qf[kk], sc); if ((kk & 3) == 3) __builtin_amdgcn_sched_barrier(0); } }
;     asm volatile("s_waitcnt lgkmcnt(0)" ::: "memory"); __builtin_amdgcn_s_barrier(); asm volatile("" ::: "memory");
	v_add_u32_e32 v25, 0, v191
	v_lshl_or_b32 v200, v0, 4, v1
	ds_read_b128 v[0:3], v25
	v_bitop3_b32 v6, v24, v4, s70 bitop3:0x36
	v_bitop3_b32 v4, v5, v4, 2 bitop3:0x36
	v_add_u32_e32 v26, 0, v197
	v_lshlrev_b32_e32 v201, 4, v6
	v_lshlrev_b32_e32 v202, 4, v4
	ds_read_b128 v[4:7], v26
	s_waitcnt lgkmcnt(0)
	v_mfma_f32_32x32x16_bf16 v[64:79], v[0:3], v[96:99], 0
	v_add_u32_e32 v27, 0, v199
	ds_read_b128 v[0:3], v27
	v_add_u32_e32 v28, 0, v200
	ds_read_b128 v[16:19], v28
	s_mov_b32 s50, s49
	s_mov_b32 s51, s49
	s_mov_b32 s52, s49
	v_mfma_f32_32x32x16_bf16 v[64:79], v[4:7], v[100:103], v[64:79]
	s_mov_b32 s53, s49
	s_mov_b32 s54, s49
	s_mov_b32 s55, s49
	s_mov_b32 s56, s49
	s_mov_b32 s57, s49
	s_mov_b32 s58, s49
	s_mov_b32 s0, s59
	s_waitcnt lgkmcnt(1)
	v_mfma_f32_32x32x16_bf16 v[64:79], v[0:3], v[104:107], v[64:79]
	s_mov_b32 s59, s49
	s_mov_b32 s1, s60
	s_mov_b32 s60, s49
	s_mov_b32 s61, s49
	s_mov_b32 s62, s49
	s_mov_b32 s63, s49
	v_mov_b64_e32 v[0:1], s[48:49]
	s_waitcnt lgkmcnt(0)
	v_mfma_f32_32x32x16_bf16 v[64:79], v[16:19], v[108:111], v[64:79]
	s_mov_b32 s84, 1
	v_mov_b32_e32 v183, v177
	v_mov_b32_e32 v185, v177
	v_mov_b64_e32 v[2:3], s[50:51]
	v_mov_b64_e32 v[4:5], s[52:53]
	v_mov_b64_e32 v[6:7], s[54:55]
	v_mov_b64_e32 v[8:9], s[56:57]
	v_mov_b64_e32 v[10:11], s[58:59]
	v_mov_b64_e32 v[12:13], s[60:61]
	v_mov_b64_e32 v[14:15], s[62:63]
	s_mov_b32 s62, 0xfffdc000
	s_movk_i32 s61, 0x180
	s_mov_b32 s60, s1
	s_mov_b32 s59, s0
	ds_read_b128 v[16:19], v25 offset:128
	ds_read_b128 v[20:23], v26 offset:128
	s_waitcnt lgkmcnt(1)
	v_mfma_f32_32x32x16_bf16 v[64:79], v[16:19], v[112:115], v[64:79]
	s_waitcnt lgkmcnt(0)
	v_mfma_f32_32x32x16_bf16 v[64:79], v[20:23], v[116:119], v[64:79]
	ds_read_b128 v[16:19], v27 offset:128
	ds_read_b128 v[20:23], v28 offset:128
	s_waitcnt lgkmcnt(1)
	v_mfma_f32_32x32x16_bf16 v[64:79], v[16:19], v[120:123], v[64:79]
	s_waitcnt lgkmcnt(0)
	v_mfma_f32_32x32x16_bf16 v[64:79], v[20:23], v[124:127], v[64:79]
	ds_read_b128 v[16:19], v25 offset:256
	ds_read_b128 v[20:23], v26 offset:256
	s_waitcnt lgkmcnt(1)
	v_mfma_f32_32x32x16_bf16 v[64:79], v[16:19], v[128:131], v[64:79]
	s_waitcnt lgkmcnt(0)
	v_mfma_f32_32x32x16_bf16 v[64:79], v[20:23], v[132:135], v[64:79]
	ds_read_b128 v[16:19], v27 offset:256
	ds_read_b128 v[20:23], v28 offset:256
	s_waitcnt lgkmcnt(1)
	v_mfma_f32_32x32x16_bf16 v[64:79], v[16:19], v[136:139], v[64:79]
	s_waitcnt lgkmcnt(0)
	v_mfma_f32_32x32x16_bf16 v[80:95], v[20:23], v[140:143], v[64:79]
	s_waitcnt lgkmcnt(0)
	s_barrier
	v_lshlrev_b32_e32 v198, 2, v24
	s_lshl_b32 s50, s40, 7
	v_readlane_b32 s0, v255, 54
	v_mov_b64_e32 v[30:31], v[14:15]
	v_mov_b64_e32 v[46:47], v[14:15]
	v_mov_b64_e32 v[62:63], v[14:15]
	v_lshl_add_u32 v203, v180, 7, 0
	s_mov_b32 s32, 0x12000
	v_add3_u32 v225, v203, v201, s32
	v_add3_u32 v245, v203, v202, s32
	s_add_i32 s51, s0, s50
	v_mov_b32_e32 v204, 0xf149f2ca
	v_mov_b32_e32 v226, 0
	v_mov_b32_e32 v227, v226
	v_mov_b32_e32 v228, v226
	v_mov_b32_e32 v229, v226
	v_mov_b32_e32 v230, v226
	v_mov_b32_e32 v231, v226
	v_mov_b32_e32 v232, v226
	v_mov_b32_e32 v233, v226
	v_mov_b32_e32 v234, v226
	v_mov_b32_e32 v235, v226
	v_mov_b32_e32 v236, v226
	v_mov_b32_e32 v237, v226
	v_mov_b32_e32 v238, v226
	v_mov_b32_e32 v239, v226
	v_mov_b32_e32 v240, v226
	v_mov_b32_e32 v241, v226
	v_mov_b32_e32 v242, 0xff7fffff
	v_mov_b32_e32 v243, 0
	v_mov_b64_e32 v[28:29], v[12:13]
	v_mov_b64_e32 v[26:27], v[10:11]
	v_mov_b64_e32 v[24:25], v[8:9]
	v_mov_b64_e32 v[22:23], v[6:7]
	v_mov_b64_e32 v[20:21], v[4:5]
	v_mov_b64_e32 v[18:19], v[2:3]
	v_mov_b64_e32 v[16:17], v[0:1]
	v_mov_b64_e32 v[44:45], v[12:13]
	v_mov_b64_e32 v[42:43], v[10:11]
	v_mov_b64_e32 v[40:41], v[8:9]
	v_mov_b64_e32 v[38:39], v[6:7]
	v_mov_b64_e32 v[36:37], v[4:5]
	v_mov_b64_e32 v[34:35], v[2:3]
	v_mov_b64_e32 v[32:33], v[0:1]
	v_mov_b64_e32 v[60:61], v[12:13]
	v_mov_b64_e32 v[58:59], v[10:11]
	v_mov_b64_e32 v[56:57], v[8:9]
	v_mov_b64_e32 v[54:55], v[6:7]
	v_mov_b64_e32 v[52:53], v[4:5]
	v_mov_b64_e32 v[50:51], v[2:3]
	v_mov_b64_e32 v[48:49], v[0:1]
	v_mov_b32_e32 v190, v177
	s_mov_b32 s0, s49
	s_mov_b32 s53, 2
	s_cmp_lt_i32 s51, 0
	s_mov_b32 s54, s0
	s_cbranch_scc1 .LBB0_477

; __device__ __forceinline__ unsigned pk2(float a, float b) { f32x2_t v = {a, b}; bf16x2v_t r = __builtin_convertvector(v, bf16x2v_t); return __builtin_bit_cast(unsigned, r); }
; #define LAS __attribute__((address_space(3)))
; __device__ __forceinline__ void attn_unit(LAS unsigned char* lds, const bf16_t* Qg, const bf16_t* Kg, const bf16_t* Vtg, bf16_t* Og, int bh, int qb, int tid_, int wave, int lane_) {
;     ...
;         float ps = 0.f; u32x4 p0, p1;
; #pragma unroll
;         for (int q = 0; q < 4; ++q) sn = MFMA32(fb[q], qf[4 + q], sn);
; #pragma unroll
;         for (int i = 0; i < 8; ++i) { sc[i] = __builtin_amdgcn_exp2f(sc[i] - mrun); ps += sc[i]; }
;         p0.x = pk2(sc[0], sc[1]); p0.y = pk2(sc[2], sc[3]); p0.z = pk2(sc[4], sc[5]); p0.w = pk2(sc[6], sc[7]);
;         __builtin_amdgcn_sched_barrier(0);
; #pragma unroll
;         for (int dt = 0; dt < 4; ++dt) fb[dt] = *(const LAS bf16x8*)(vb + vro[0] + dt * 4096);
;         __builtin_amdgcn_sched_barrier(0);
;         ATT_ISSUE_K(j3, s0);
;         __builtin_amdgcn_sched_barrier(0);
; #pragma unroll
;         for (int q = 0; q < 4; ++q) sn = MFMA32(fa[q], qf[8 + q], sn);
; #pragma unroll
;         for (int i = 8; i < 12; ++i) { sc[i] = __builtin_amdgcn_exp2f(sc[i] - mrun); ps += sc[i]; }
;         p1.x = pk2(sc[8], sc[9]); p1.y = pk2(sc[10], sc[11]);
;         __builtin_amdgcn_sched_barrier(0);
;         ATT_ISSUE_V(j2, s2);
;         __builtin_amdgcn_sched_barrier(0);
; #pragma unroll
;         for (int dt = 0; dt < 4; ++dt) fa[dt] = *(const LAS bf16x8*)(vb + vro[1] + dt * 4096);
;         { const bf16x8 pf0 = __builtin_bit_cast(bf16x8, p0);
;           o[0] = MFMA32(fb[0], pf0, o[0]); o[1] = MFMA32(fb[1], pf0, o[1]); o[2] = MFMA32(fb[2], pf0, o[2]); o[3] = MFMA32(fb[3], pf0, o[3]); }
; #pragma unroll
;         for (int i = 12; i < 16; ++i) { sc[i] = __builtin_amdgcn_exp2f(sc[i] - mrun); ps += sc[i]; }
;         p1.z = pk2(sc[12], sc[13]); p1.w = pk2(sc[14], sc[15]);
;         lrun += ps;
;         __builtin_amdgcn_sched_barrier(0);
;         { const bf16x8 pf1 = __builtin_bit_cast(bf16x8, p1);
;           o[0] = MFMA32(fa[0], pf1, o[0]); o[1] = MFMA32(fa[1], pf1, o[1]); o[2] = MFMA32(fa[2], pf1, o[2]); o[3] = MFMA32(fa[3], pf1, o[3]); }
;         asm volatile("s_waitcnt vmcnt(5) lgkmcnt(0)" ::: "memory"); __builtin_amdgcn_s_barrier(); asm volatile("" ::: "memory");
.LBB0_480:
	v_mfma_f32_32x32x16_bf16 v[64:79], v[164:167], v[112:115], v[64:79]
	v_exp_f32_e32 v192, v80
	v_exp_f32_e32 v193, v81
	v_exp_f32_e32 v194, v82
	s_waitcnt lgkmcnt(0)
	v_mfma_f32_32x32x16_bf16 v[64:79], v[172:175], v[116:119], v[64:79]
	v_exp_f32_e32 v205, v83
	v_exp_f32_e32 v206, v84
	v_exp_f32_e32 v207, v85
	v_exp_f32_e32 v208, v86
	v_mfma_f32_32x32x16_bf16 v[64:79], v[168:171], v[120:123], v[64:79]
	s_add_i32 s0, s52, 3
	v_exp_f32_e32 v209, v87
	s_cmp_lt_u32 s0, s89
	s_cselect_b32 s0, s0, s45
	s_add_i32 s1, s52, 2
	s_cmp_lt_u32 s52, s44
	s_cselect_b32 s48, s1, s45
	v_cvt_pk_bf16_f32 v246, v192, v193
	v_cvt_pk_bf16_f32 v247, v194, v205
	v_cvt_pk_bf16_f32 v248, v206, v207
	v_cvt_pk_bf16_f32 v249, v208, v209
	v_lshl_add_u32 v172, s54, 14, v225
	ds_read_b128 v[214:217], v172
	ds_read_b128 v[164:167], v172 offset:4096
	ds_read_b128 v[168:171], v172 offset:8192
	ds_read_b128 v[172:175], v172 offset:12288
	v_add_f32_e32 v192, v193, v192
	v_add_f32_e32 v192, v194, v192
	v_add_f32_e32 v192, v205, v192
	v_add_f32_e32 v192, v206, v192
	v_add_f32_e32 v192, v207, v192
	v_add_f32_e32 v192, v208, v192
	v_add_f32_e32 v194, v209, v192
	s_mul_hi_u32 s1, s0, 0x6000
	s_mulk_i32 s0, 0x6000
	s_add_u32 s0, s92, s0
	s_mul_i32 s4, s54, 0x6000
	s_addc_u32 s1, s93, s1
	s_add_i32 s4, s71, s4
	s_mov_b32 m0, s4
	s_waitcnt lgkmcnt(5)
	v_mfma_f32_32x32x16_bf16 v[64:79], v[160:163], v[124:127], v[64:79]
	global_load_lds_dwordx4 v176, s[0:1]
	s_add_i32 m0, s4, 0x400
	s_nop 0
	global_load_lds_dwordx4 v182, s[0:1]
	s_add_i32 m0, s4, 0x800
	s_nop 0
	global_load_lds_dwordx4 v184, s[0:1]
	v_mfma_f32_32x32x16_bf16 v[64:79], v[148:151], v[128:131], v[64:79]
	v_exp_f32_e32 v220, v88
	v_exp_f32_e32 v221, v89
	v_exp_f32_e32 v222, v90
	v_mfma_f32_32x32x16_bf16 v[64:79], v[156:159], v[132:135], v[64:79]
	v_exp_f32_e32 v223, v91
	v_add_f32_e32 v148, v220, v194
	v_add_f32_e32 v148, v221, v148
	v_add_f32_e32 v148, v222, v148
	v_add_f32_e32 v156, v223, v148
	v_cvt_pk_bf16_f32 v250, v220, v221
	v_cvt_pk_bf16_f32 v251, v222, v223
	v_mfma_f32_32x32x16_bf16 v[64:79], v[152:155], v[136:139], v[64:79]
	v_exp_f32_e32 v220, v92
	v_exp_f32_e32 v221, v93
	v_exp_f32_e32 v222, v94
	v_exp_f32_e32 v223, v95
	s_waitcnt lgkmcnt(0)
	v_mfma_f32_32x32x16_bf16 v[80:95], v[144:147], v[140:143], v[64:79]
	s_lshl_b64 s[0:1], s[48:49], 7
	s_add_u32 s0, s94, s0
	s_addc_u32 s1, s95, s1
	s_lshl_b32 s4, s53, 14
	s_add_i32 s4, s4, 0
	s_add_i32 s4, s4, s68
	s_add_i32 m0, s4, 0x12000
	s_nop 0
	global_load_lds_dwordx4 v186, s[0:1]
	s_add_i32 m0, s4, 0x12400
	s_nop 0
	global_load_lds_dwordx4 v188, s[0:1]
	v_lshl_add_u32 v219, s54, 14, v245
	v_mfma_f32_32x32x16_bf16 v[48:63], v[214:217], v[246:249], v[48:63]
	ds_read_b128 v[214:217], v219
	ds_read_b128 v[144:147], v219 offset:4096
	ds_read_b128 v[148:151], v219 offset:8192
	ds_read_b128 v[152:155], v219 offset:12288
	v_mfma_f32_32x32x16_bf16 v[32:47], v[164:167], v[246:249], v[32:47]
	v_add_f32_e32 v213, v220, v156
	v_add_f32_e32 v213, v221, v213
	v_add_f32_e32 v213, v222, v213
	v_add_f32_e32 v213, v223, v213
	v_add_f32_e32 v190, v190, v213
	v_mfma_f32_32x32x16_bf16 v[16:31], v[168:171], v[246:249], v[16:31]
	v_cvt_pk_bf16_f32 v252, v220, v221
	v_cvt_pk_bf16_f32 v253, v222, v223
	v_mfma_f32_32x32x16_bf16 v[0:15], v[172:175], v[246:249], v[0:15]
	s_waitcnt lgkmcnt(0)
	v_mfma_f32_32x32x16_bf16 v[48:63], v[214:217], v[250:253], v[48:63]
	s_waitcnt vmcnt(5) lgkmcnt(0)
	s_barrier
	s_add_i32 s52, s52, 1
	s_add_i32 s51, s51, 64
	s_cmp_eq_u32 s89, s52
	v_mfma_f32_32x32x16_bf16 v[32:47], v[144:147], v[250:253], v[32:47]
	v_mfma_f32_32x32x16_bf16 v[16:31], v[148:151], v[250:253], v[16:31]
	v_mfma_f32_32x32x16_bf16 v[0:15], v[152:155], v[250:253], v[0:15]
	s_cbranch_scc1 .LBB0_482
	s_mov_b32 s0, s84
	s_mov_b32 s84, s53
	s_mov_b32 s53, s54
	s_cmp_lt_i32 s51, 0
	s_mov_b32 s54, s0
	s_cbranch_scc0 .LBB0_476
	s_branch .LBB0_477

; #define ATT_ISSUE_K(jt, stage) do { _Pragma("unroll") for (int i_ = 0; i_ < 3; ++i_) ATT_DMA(kg + (size_t)(jt) * KTILE + kgo[i_], KRING + (stage) * KTILE + (wave * 3 + i_) * 1024); } while (0)
; #define ATT_ISSUE_V(jt, stage) do { _Pragma("unroll") for (int i_ = 0; i_ < 2; ++i_) ATT_DMA(vg + (size_t)(jt) * 128 + vgo[i_], VRING + (stage) * VTILE + (wave * 2 + i_) * 1024); } while (0)
; __device__ __forceinline__ void attn_unit(LAS unsigned char* lds, const bf16_t* Qg, const bf16_t* Kg, const bf16_t* Vtg, bf16_t* Og, int bh, int qb, int tid_, int wave, int lane_) {
;     ...
;     { const bf16_t* qp = Qg + ((size_t)bh * SEQ + 128 * qb + 32 * rg + r) * QKD + 8 * hi;
; #pragma unroll
;       for (int kk = 0; kk < 12; ++kk) qf[kk] = *(const bf16x8*)(qp + 16 * kk); }
;     const unsigned char* kg = (const unsigned char*)(Kg + (size_t)bh * SEQ * QKD);
;     const unsigned char* vg = (const unsigned char*)(Vtg + (size_t)bh * VD * SEQ);
;     unsigned kgo[3], vgo[2];
; #pragma unroll
;     for (int i = 0; i < 3; ++i) { const int a = (wave * 3 + i) * 1024 + lane * 16, row = a / 384, cp = (a % 384) >> 4, cl = (cp & ~7) | ((cp ^ (row >> 1)) & 7); kgo[i] = (unsigned)(row * 384 + cl * 16); }
; #pragma unroll
;     for (int i = 0; i < 2; ++i) { const int a = (wave * 2 + i) * 1024 + lane * 16, row = a >> 7, cp = (a & 127) >> 4, cl = (cp ^ (row >> 1)) & 7; vgo[i] = (unsigned)(row * (SEQ * 2) + cl * 16); }
;     const int sw = (r >> 1) & 7;
;     unsigned kro[4], vro[2];
; #pragma unroll
;     for (int q = 0; q < 4; ++q) kro[q] = (unsigned)((32 * kh + r) * 384 + (((2 * q + hi) ^ sw) * 16));
; #pragma unroll
;     for (int s = 0; s < 2; ++s) vro[s] = (unsigned)(VRING + r * 128 + (((4 * kh + 2 * s + hi) ^ sw) * 16));
;     f32x16 o[4]; float mrun = NEG, lrun = 0.f;
; #pragma unroll
;     for (int dt = 0; dt < 4; ++dt)
; #pragma unroll
;         for (int i = 0; i < 16; ++i) o[dt][i] = 0.f;
;     ATT_ISSUE_K(0, 0); ATT_ISSUE_V(0, 0); ATT_ISSUE_K(1, 1);
;     ATT_ISSUE_K((2 < nt) ? 2 : nt - 1, 2); ATT_ISSUE_V(1, 1);
;     asm volatile("s_waitcnt vmcnt(5)" ::: "memory"); __builtin_amdgcn_s_barrier(); asm volatile("" ::: "memory");
.LBB0_486:
	s_lshl_b32 s52, s40, 1
	s_ashr_i32 s51, s50, 31
	v_mov_b32_e32 v6, v254
	s_add_u32 s0, s41, s50
	s_barrier
	s_addc_u32 s12, 0, s51
	v_and_b32_e32 v191, 31, v6
	s_or_b32 s0, s0, s97
	v_or_b32_e32 v2, s0, v191
	v_readlane_b32 s0, v255, 36
	v_readlane_b32 s1, v255, 37
	v_bfe_u32 v190, v6, 5, 1
	v_lshlrev_b32_e32 v176, 4, v190
	v_mov_b64_e32 v[0:1], s[0:1]
	v_mad_u64_u32 v[0:1], s[0:1], v2, s61, v[0:1]
	v_mad_i32_i24 v1, s12, v195, v1
	v_and_b32_e32 v181, 63, v6
	v_lshl_add_u64 v[0:1], v[0:1], 0, v[176:177]
	global_load_dwordx4 v[96:99], v[0:1], off
	global_load_dwordx4 v[100:103], v[0:1], off offset:32
	global_load_dwordx4 v[104:107], v[0:1], off offset:64
	global_load_dwordx4 v[108:111], v[0:1], off offset:96
	global_load_dwordx4 v[112:115], v[0:1], off offset:128
	global_load_dwordx4 v[116:119], v[0:1], off offset:160
	global_load_dwordx4 v[120:123], v[0:1], off offset:192
	global_load_dwordx4 v[124:127], v[0:1], off offset:224
	global_load_dwordx4 v[128:131], v[0:1], off offset:256
	global_load_dwordx4 v[132:135], v[0:1], off offset:288
	global_load_dwordx4 v[136:139], v[0:1], off offset:320
	global_load_dwordx4 v[140:143], v[0:1], off offset:352
	v_lshlrev_b32_e32 v0, 4, v181
	v_or_b32_e32 v1, s59, v0
	v_mul_hi_i32 v2, v1, s42
	v_lshrrev_b32_e32 v3, 31, v2
	v_ashrrev_i32_e32 v2, 6, v2
	v_add_u32_e32 v2, v2, v3
	v_mul_i32_i24_e32 v3, 0x180, v2
	v_lshlrev_b32_e32 v2, 3, v2
	v_sub_u32_e32 v1, v1, v3
	v_and_b32_e32 v2, 0x70, v2
	v_xad_u32 v182, v2, v1, v3
	v_or_b32_e32 v1, s60, v0
	v_mul_hi_i32 v2, v1, s42
	v_lshrrev_b32_e32 v3, 31, v2
	v_ashrrev_i32_e32 v2, 6, v2
	v_add_u32_e32 v2, v2, v3
	v_mul_i32_i24_e32 v3, 0x180, v2
	v_lshlrev_b32_e32 v2, 3, v2
	v_sub_u32_e32 v1, v1, v3
	v_and_b32_e32 v2, 0x70, v2
	v_xad_u32 v184, v2, v1, v3
	v_or_b32_e32 v1, s67, v0
	v_mul_hi_i32 v2, v1, s42
	v_lshrrev_b32_e32 v3, 31, v2
	v_ashrrev_i32_e32 v2, 6, v2
	v_add_u32_e32 v2, v2, v3
	v_mul_i32_i24_e32 v3, 0x180, v2
	v_lshlrev_b32_e32 v2, 3, v2
	v_sub_u32_e32 v1, v1, v3
	v_and_b32_e32 v2, 0x70, v2
	v_xad_u32 v186, v2, v1, v3
	v_or_b32_e32 v0, s68, v0
	v_lshlrev_b32_e32 v2, 4, v6
	v_and_b32_e32 v3, 48, v6
	s_mov_b32 m0, s71
	v_lshlrev_b32_e32 v1, 7, v0
	v_bitop3_b32 v2, v2, v3, s86 bitop3:0x6c
	v_or_b32_e32 v0, 0x400, v0
	v_and_or_b32 v176, v1, s62, v2
	v_lshrrev_b32_e32 v1, 8, v0
	global_load_lds_dwordx4 v182, s[92:93]
	s_mov_b32 m0, s91
	v_xor_b32_e32 v1, v1, v6
	v_lshlrev_b32_e32 v0, 7, v0
	global_load_lds_dwordx4 v184, s[92:93]
	s_mov_b32 m0, s74
	v_and_b32_e32 v0, 0xffffc000, v0
	v_lshlrev_b32_e32 v1, 4, v1
	global_load_lds_dwordx4 v186, s[92:93]
	s_mov_b32 m0, s96
	s_or_b32 s44, s52, 1
	v_and_or_b32 v188, v1, s86, v0
	global_load_lds_dwordx4 v176, s[94:95]
	s_mov_b32 m0, s43
	s_cmp_lt_i32 s40, 1
	global_load_lds_dwordx4 v188, s[94:95]
	s_mov_b32 m0, s75
	s_cselect_b32 s0, s44, 2
	global_load_lds_dwordx4 v182, s[38:39]
	s_mov_b32 m0, s90
	s_mul_hi_i32 s1, s0, 0x6000
	s_mulk_i32 s0, 0x6000
	global_load_lds_dwordx4 v184, s[38:39]
	s_mov_b32 m0, s2
	s_add_u32 s0, s92, s0
	global_load_lds_dwordx4 v186, s[38:39]
	s_addc_u32 s1, s93, s1
	s_mov_b32 m0, s85
	v_lshl_add_u64 v[0:1], s[94:95], 0, v[176:177]
	global_load_lds_dwordx4 v182, s[0:1]
	s_mov_b32 m0, s87
	v_mov_b32_e32 v189, v177
	global_load_lds_dwordx4 v184, s[0:1]
	s_mov_b32 m0, s3
	v_lshl_add_u64 v[2:3], s[94:95], 0, v[188:189]
	global_load_lds_dwordx4 v186, s[0:1]
	v_lshl_add_u64 v[0:1], v[0:1], 0, s[78:79]
	s_mov_b32 m0, s33
	s_nop 0
	global_load_lds_dwordx4 v[0:1], off
	v_lshl_add_u64 v[0:1], v[2:3], 0, s[78:79]
	s_mov_b32 m0, s10
	s_nop 0
	global_load_lds_dwordx4 v[0:1], off
	v_lshrrev_b32_e32 v0, 1, v6
	v_or_b32_e32 v1, s69, v191
	v_mul_lo_u32 v1, v1, s61
	v_bitop3_b32 v0, v190, v0, 7 bitop3:0x78
	v_lshl_or_b32 v199, v0, 4, v1
	s_waitcnt vmcnt(5)
	s_barrier
; #define LAS __attribute__((address_space(3)))
; #define MFMA32(a, b, c) __builtin_amdgcn_mfma_f32_32x32x16_bf16((a), (b), (c), 0, 0, 0)
; #define ATT_ISSUE_K(jt, stage) do { _Pragma("unroll") for (int i_ = 0; i_ < 3; ++i_) ATT_DMA(kg + (size_t)(jt) * KTILE + kgo[i_], KRING + (stage) * KTILE + (wave * 3 + i_) * 1024); } while (0)
; #define ATT_ISSUE_V(jt, stage) do { _Pragma("unroll") for (int i_ = 0; i_ < 2; ++i_) ATT_DMA(vg + (size_t)(jt) * 128 + vgo[i_], VRING + (stage) * VTILE + (wave * 2 + i_) * 1024); } while (0)
; __device__ __forceinline__ void attn_unit(LAS unsigned char* lds, const bf16_t* Qg, const bf16_t* Kg, const bf16_t* Vtg, bf16_t* Og, int bh, int qb, int tid_, int wave, int lane_) {
;     ...
;     for (int s = 0; s < 2; ++s) vro[s] = (unsigned)(VRING + r * 128 + (((4 * kh + 2 * s + hi) ^ sw) * 16));
;     f32x16 o[4]; float mrun = NEG, lrun = 0.f;
; #pragma unroll
;     for (int dt = 0; dt < 4; ++dt)
; #pragma unroll
;         for (int i = 0; i < 16; ++i) o[dt][i] = 0.f;
;     ATT_ISSUE_K(0, 0); ATT_ISSUE_V(0, 0); ATT_ISSUE_K(1, 1);
;     ATT_ISSUE_K((2 < nt) ? 2 : nt - 1, 2); ATT_ISSUE_V(1, 1);
;     asm volatile("s_waitcnt vmcnt(5)" ::: "memory"); __builtin_amdgcn_s_barrier(); asm volatile("" ::: "memory");
;     f32x16 sc, sn;
;     {
; #pragma unroll
;       for (int i = 0; i < 16; ++i) sc[i] = 0.f;
; #pragma unroll
;       for (int kk = 0; kk < 12; ++kk) { const bf16x8 kf = *(const LAS bf16x8*)(lds + KRING + kro[kk & 3] + (kk >> 2) * 128); sc = MFMA32(kf, qf[kk], sc); if ((kk & 3) == 3) __builtin_amdgcn_sched_barrier(0); } }
;     asm volatile("s_waitcnt lgkmcnt(0)" ::: "memory"); __builtin_amdgcn_s_barrier(); asm volatile("" ::: "memory");
	v_add_u32_e32 v10, 0, v199
	ds_read_b128 v[2:5], v10
	v_bfe_u32 v0, v6, 1, 3
	v_bitop3_b32 v6, v190, v0, 2 bitop3:0x36
	v_lshl_or_b32 v200, v6, 4, v1
	v_add_u32_e32 v11, 0, v200
	ds_read_b128 v[6:9], v11
	s_waitcnt lgkmcnt(0)
	v_mfma_f32_32x32x16_bf16 v[64:79], v[2:5], v[96:99], 0
	v_bitop3_b32 v2, v190, v0, 4 bitop3:0x36
	v_lshl_or_b32 v201, v2, 4, v1
	v_add_u32_e32 v12, 0, v201
	ds_read_b128 v[2:5], v12
	v_mfma_f32_32x32x16_bf16 v[64:79], v[6:9], v[100:103], v[64:79]
	v_bitop3_b32 v6, v190, v0, 6 bitop3:0x36
	v_lshl_or_b32 v202, v6, 4, v1
	v_add_u32_e32 v1, 0, v202
	ds_read_b128 v[6:9], v1
	s_waitcnt lgkmcnt(1)
	v_mfma_f32_32x32x16_bf16 v[64:79], v[2:5], v[104:107], v[64:79]
	s_waitcnt lgkmcnt(0)
	v_mfma_f32_32x32x16_bf16 v[64:79], v[6:9], v[108:111], v[64:79]
	ds_read_b128 v[2:5], v10 offset:128
	ds_read_b128 v[6:9], v11 offset:128
	s_waitcnt lgkmcnt(1)
	v_mfma_f32_32x32x16_bf16 v[64:79], v[2:5], v[112:115], v[64:79]
	s_waitcnt lgkmcnt(0)
	v_mfma_f32_32x32x16_bf16 v[64:79], v[6:9], v[116:119], v[64:79]
	ds_read_b128 v[2:5], v12 offset:128
	ds_read_b128 v[6:9], v1 offset:128
	s_waitcnt lgkmcnt(1)
	v_mfma_f32_32x32x16_bf16 v[64:79], v[2:5], v[120:123], v[64:79]
	s_waitcnt lgkmcnt(0)
	v_mfma_f32_32x32x16_bf16 v[64:79], v[6:9], v[124:127], v[64:79]
	ds_read_b128 v[2:5], v10 offset:256
	ds_read_b128 v[6:9], v11 offset:256
	s_waitcnt lgkmcnt(1)
	v_mfma_f32_32x32x16_bf16 v[64:79], v[2:5], v[128:131], v[64:79]
	s_waitcnt lgkmcnt(0)
	v_mfma_f32_32x32x16_bf16 v[64:79], v[6:9], v[132:135], v[64:79]
	ds_read_b128 v[2:5], v12 offset:256
	ds_read_b128 v[6:9], v1 offset:256
	s_waitcnt lgkmcnt(1)
	v_mfma_f32_32x32x16_bf16 v[64:79], v[2:5], v[136:139], v[64:79]
	s_waitcnt lgkmcnt(0)
	v_mfma_f32_32x32x16_bf16 v[80:95], v[6:9], v[140:143], v[64:79]
	s_waitcnt lgkmcnt(0)
	s_barrier
	s_cmp_lt_i32 s40, 0
	s_cbranch_scc1 .LBB0_494
	v_or_b32_e32 v1, s70, v190
	v_bitop3_b32 v2, v190, v0, s70 bitop3:0x36
	v_bitop3_b32 v0, v1, v0, 2 bitop3:0x36
	v_mov_b32_e32 v14, v177
	v_mov_b32_e32 v15, v177
	v_lshlrev_b32_e32 v203, 4, v2
	v_lshlrev_b32_e32 v204, 4, v0
	v_mov_b32_e32 v0, v177
	v_mov_b32_e32 v1, v177
	v_mov_b32_e32 v2, v177
	v_mov_b32_e32 v3, v177
	v_mov_b32_e32 v4, v177
	v_mov_b32_e32 v5, v177
	v_mov_b32_e32 v6, v177
	v_mov_b32_e32 v7, v177
	v_mov_b32_e32 v8, v177
	v_mov_b32_e32 v9, v177
	v_mov_b32_e32 v10, v177
	v_mov_b32_e32 v11, v177
	v_mov_b32_e32 v12, v177
	v_mov_b32_e32 v13, v177
	v_mov_b64_e32 v[30:31], v[14:15]
	v_mov_b64_e32 v[46:47], v[14:15]
	v_mov_b64_e32 v[62:63], v[14:15]
	v_mov_b32_e32 v183, v177
	v_mov_b32_e32 v185, v177
	v_mov_b32_e32 v187, v177
	s_mov_b32 s53, 2
	s_add_i32 s45, s52, 2
	v_lshlrev_b32_e32 v205, 2, v190
	v_lshl_add_u32 v206, v191, 7, 0
	s_mov_b32 s32, 0x12000
	v_add3_u32 v225, v206, v203, s32
	v_add3_u32 v245, v206, v204, s32
	s_sub_i32 s54, s69, s50
	s_mov_b32 s0, 0
	s_mov_b32 s55, 1
	v_mov_b32_e32 v198, 0xf149f2ca
	v_mov_b32_e32 v226, 0
	v_mov_b32_e32 v227, v226
	v_mov_b32_e32 v228, v226
	v_mov_b32_e32 v229, v226
	v_mov_b32_e32 v230, v226
	v_mov_b32_e32 v231, v226
	v_mov_b32_e32 v232, v226
	v_mov_b32_e32 v233, v226
	v_mov_b32_e32 v234, v226
	v_mov_b32_e32 v235, v226
	v_mov_b32_e32 v236, v226
	v_mov_b32_e32 v237, v226
	v_mov_b32_e32 v238, v226
	v_mov_b32_e32 v239, v226
	v_mov_b32_e32 v240, v226
	v_mov_b32_e32 v241, v226
	v_mov_b32_e32 v242, 0xff7fffff
	v_mov_b32_e32 v243, 0
	v_mov_b32_e32 v180, 0
	v_readlane_b32 s56, v255, 55
	v_mov_b64_e32 v[28:29], v[12:13]
	v_mov_b64_e32 v[26:27], v[10:11]
	v_mov_b64_e32 v[24:25], v[8:9]
	v_mov_b64_e32 v[22:23], v[6:7]
	v_mov_b64_e32 v[20:21], v[4:5]
	v_mov_b64_e32 v[18:19], v[2:3]
	v_mov_b64_e32 v[16:17], v[0:1]
	v_mov_b64_e32 v[44:45], v[12:13]
	v_mov_b64_e32 v[42:43], v[10:11]
	v_mov_b64_e32 v[40:41], v[8:9]
	v_mov_b64_e32 v[38:39], v[6:7]
	v_mov_b64_e32 v[36:37], v[4:5]
	v_mov_b64_e32 v[34:35], v[2:3]
	v_mov_b64_e32 v[32:33], v[0:1]
	v_mov_b64_e32 v[60:61], v[12:13]
	v_mov_b64_e32 v[58:59], v[10:11]
	v_mov_b64_e32 v[56:57], v[8:9]
	v_mov_b64_e32 v[54:55], v[6:7]
	v_mov_b64_e32 v[52:53], v[4:5]
	v_mov_b64_e32 v[50:51], v[2:3]
	v_mov_b64_e32 v[48:49], v[0:1]
	s_mov_b32 s57, 0
	s_mov_b64 s[88:89], s[8:9]
	s_add_i32 s1, s54, s56
	s_cmp_lt_i32 s1, 0
	s_mov_b32 s58, s0
	s_cbranch_scc1 .LBB0_489

; __device__ __forceinline__ unsigned pk2(float a, float b) { f32x2_t v = {a, b}; bf16x2v_t r = __builtin_convertvector(v, bf16x2v_t); return __builtin_bit_cast(unsigned, r); }
; #define LAS __attribute__((address_space(3)))
; __device__ __forceinline__ void attn_unit(LAS unsigned char* lds, const bf16_t* Qg, const bf16_t* Kg, const bf16_t* Vtg, bf16_t* Og, int bh, int qb, int tid_, int wave, int lane_) {
;     ...
;         float ps = 0.f; u32x4 p0, p1;
; #pragma unroll
;         for (int q = 0; q < 4; ++q) sn = MFMA32(fb[q], qf[4 + q], sn);
; #pragma unroll
;         for (int i = 0; i < 8; ++i) { sc[i] = __builtin_amdgcn_exp2f(sc[i] - mrun); ps += sc[i]; }
;         p0.x = pk2(sc[0], sc[1]); p0.y = pk2(sc[2], sc[3]); p0.z = pk2(sc[4], sc[5]); p0.w = pk2(sc[6], sc[7]);
;         __builtin_amdgcn_sched_barrier(0);
; #pragma unroll
;         for (int dt = 0; dt < 4; ++dt) fb[dt] = *(const LAS bf16x8*)(vb + vro[0] + dt * 4096);
;         __builtin_amdgcn_sched_barrier(0);
;         ATT_ISSUE_K(j3, s0);
;         __builtin_amdgcn_sched_barrier(0);
; #pragma unroll
;         for (int q = 0; q < 4; ++q) sn = MFMA32(fa[q], qf[8 + q], sn);
; #pragma unroll
;         for (int i = 8; i < 12; ++i) { sc[i] = __builtin_amdgcn_exp2f(sc[i] - mrun); ps += sc[i]; }
;         p1.x = pk2(sc[8], sc[9]); p1.y = pk2(sc[10], sc[11]);
;         __builtin_amdgcn_sched_barrier(0);
;         ATT_ISSUE_V(j2, s2);
;         __builtin_amdgcn_sched_barrier(0);
; #pragma unroll
;         for (int dt = 0; dt < 4; ++dt) fa[dt] = *(const LAS bf16x8*)(vb + vro[1] + dt * 4096);
;         { const bf16x8 pf0 = __builtin_bit_cast(bf16x8, p0);
;           o[0] = MFMA32(fb[0], pf0, o[0]); o[1] = MFMA32(fb[1], pf0, o[1]); o[2] = MFMA32(fb[2], pf0, o[2]); o[3] = MFMA32(fb[3], pf0, o[3]); }
; #pragma unroll
;         for (int i = 12; i < 16; ++i) { sc[i] = __builtin_amdgcn_exp2f(sc[i] - mrun); ps += sc[i]; }
;         p1.z = pk2(sc[12], sc[13]); p1.w = pk2(sc[14], sc[15]);
;         lrun += ps;
;         __builtin_amdgcn_sched_barrier(0);
;         { const bf16x8 pf1 = __builtin_bit_cast(bf16x8, p1);
;           o[0] = MFMA32(fa[0], pf1, o[0]); o[1] = MFMA32(fa[1], pf1, o[1]); o[2] = MFMA32(fa[2], pf1, o[2]); o[3] = MFMA32(fa[3], pf1, o[3]); }
;         asm volatile("s_waitcnt vmcnt(5) lgkmcnt(0)" ::: "memory"); __builtin_amdgcn_s_barrier(); asm volatile("" ::: "memory");
.LBB0_492:
	v_mfma_f32_32x32x16_bf16 v[64:79], v[164:167], v[112:115], v[64:79]
	v_exp_f32_e32 v192, v80
	v_exp_f32_e32 v193, v81
	v_exp_f32_e32 v194, v82
	s_waitcnt lgkmcnt(0)
	v_mfma_f32_32x32x16_bf16 v[64:79], v[172:175], v[116:119], v[64:79]
	v_exp_f32_e32 v207, v83
	v_exp_f32_e32 v208, v84
	v_exp_f32_e32 v209, v85
	v_exp_f32_e32 v210, v86
	v_mfma_f32_32x32x16_bf16 v[64:79], v[168:171], v[120:123], v[64:79]
	s_add_i32 s0, s57, 3
	v_exp_f32_e32 v211, v87
	s_cmp_lt_i32 s0, s45
	s_cselect_b32 s0, s0, s44
	s_add_i32 s1, s57, 2
	s_cmp_lt_i32 s57, s52
	s_cselect_b32 s48, s1, s44
	v_cvt_pk_bf16_f32 v246, v192, v193
	v_cvt_pk_bf16_f32 v247, v194, v207
	v_cvt_pk_bf16_f32 v248, v208, v209
	v_cvt_pk_bf16_f32 v249, v210, v211
	v_lshl_add_u32 v172, s58, 14, v225
	ds_read_b128 v[214:217], v172
	ds_read_b128 v[164:167], v172 offset:4096
	ds_read_b128 v[168:171], v172 offset:8192
	ds_read_b128 v[172:175], v172 offset:12288
	v_add_f32_e32 v192, v193, v192
	v_add_f32_e32 v192, v194, v192
	v_add_f32_e32 v192, v207, v192
	v_add_f32_e32 v192, v208, v192
	v_add_f32_e32 v192, v209, v192
	v_add_f32_e32 v192, v210, v192
	v_add_f32_e32 v194, v211, v192
	s_mul_hi_u32 s1, s0, 0x6000
	s_mulk_i32 s0, 0x6000
	s_add_u32 s0, s92, s0
	s_mul_i32 s12, s58, 0x6000
	s_addc_u32 s1, s93, s1
	s_add_i32 s12, s71, s12
	s_mov_b32 m0, s12
	s_waitcnt lgkmcnt(5)
	v_mfma_f32_32x32x16_bf16 v[64:79], v[160:163], v[124:127], v[64:79]
	global_load_lds_dwordx4 v182, s[0:1]
	s_add_i32 m0, s12, 0x400
	s_nop 0
	global_load_lds_dwordx4 v184, s[0:1]
	s_add_i32 m0, s12, 0x800
	s_nop 0
	global_load_lds_dwordx4 v186, s[0:1]
	v_mfma_f32_32x32x16_bf16 v[64:79], v[148:151], v[128:131], v[64:79]
	v_exp_f32_e32 v220, v88
	v_exp_f32_e32 v221, v89
	v_exp_f32_e32 v222, v90
	v_mfma_f32_32x32x16_bf16 v[64:79], v[156:159], v[132:135], v[64:79]
	v_exp_f32_e32 v223, v91
	v_add_f32_e32 v148, v220, v194
	v_add_f32_e32 v148, v221, v148
	v_add_f32_e32 v148, v222, v148
	v_add_f32_e32 v156, v223, v148
	v_cvt_pk_bf16_f32 v250, v220, v221
	v_cvt_pk_bf16_f32 v251, v222, v223
	v_mfma_f32_32x32x16_bf16 v[64:79], v[152:155], v[136:139], v[64:79]
	v_exp_f32_e32 v220, v92
	v_exp_f32_e32 v221, v93
	v_exp_f32_e32 v222, v94
	v_exp_f32_e32 v223, v95
	s_waitcnt lgkmcnt(0)
	v_mfma_f32_32x32x16_bf16 v[80:95], v[144:147], v[140:143], v[64:79]
	s_lshl_b64 s[0:1], s[48:49], 7
	s_add_u32 s0, s94, s0
	s_addc_u32 s1, s95, s1
	s_lshl_b32 s12, s53, 14
	s_add_i32 s12, s12, 0
	s_add_i32 s12, s12, s68
	s_add_i32 m0, s12, 0x12000
	s_nop 0
	global_load_lds_dwordx4 v176, s[0:1]
	s_add_i32 m0, s12, 0x12400
	s_nop 0
	global_load_lds_dwordx4 v188, s[0:1]
	v_lshl_add_u32 v219, s58, 14, v245
	v_mfma_f32_32x32x16_bf16 v[48:63], v[214:217], v[246:249], v[48:63]
	ds_read_b128 v[214:217], v219
	ds_read_b128 v[144:147], v219 offset:4096
	ds_read_b128 v[148:151], v219 offset:8192
	ds_read_b128 v[152:155], v219 offset:12288
	v_mfma_f32_32x32x16_bf16 v[32:47], v[164:167], v[246:249], v[32:47]
	v_add_f32_e32 v213, v220, v156
	v_add_f32_e32 v213, v221, v213
	v_add_f32_e32 v213, v222, v213
	v_add_f32_e32 v213, v223, v213
	v_add_f32_e32 v180, v180, v213
	v_mfma_f32_32x32x16_bf16 v[16:31], v[168:171], v[246:249], v[16:31]
	v_cvt_pk_bf16_f32 v252, v220, v221
	v_cvt_pk_bf16_f32 v253, v222, v223
	v_mfma_f32_32x32x16_bf16 v[0:15], v[172:175], v[246:249], v[0:15]
	s_waitcnt lgkmcnt(0)
	v_mfma_f32_32x32x16_bf16 v[48:63], v[214:217], v[250:253], v[48:63]
	s_waitcnt vmcnt(5) lgkmcnt(0)
	s_barrier
	s_add_i32 s57, s57, 1
	s_add_i32 s56, s56, 64
	s_cmp_eq_u32 s45, s57
	v_mfma_f32_32x32x16_bf16 v[32:47], v[144:147], v[250:253], v[32:47]
	v_mfma_f32_32x32x16_bf16 v[16:31], v[148:151], v[250:253], v[16:31]
	v_mfma_f32_32x32x16_bf16 v[0:15], v[152:155], v[250:253], v[0:15]
	s_cbranch_scc1 .LBB0_495
	s_mov_b32 s0, s55
	s_mov_b32 s55, s53
	s_mov_b32 s53, s58
	s_add_i32 s1, s54, s56
	s_cmp_lt_i32 s1, 0
	s_mov_b32 s58, s0
	s_cbranch_scc0 .LBB0_488
	s_branch .LBB0_489

; __device__ __forceinline__ void unpack8(const u32x4 v, float (&f)[8]) { f[0] = bflo(v.x); f[1] = bfhi(v.x); f[2] = bflo(v.y); f[3] = bfhi(v.y); f[4] = bflo(v.z); f[5] = bfhi(v.z); f[6] = bflo(v.w); f[7] = bfhi(v.w); }
; __device__ __forceinline__ void phase6(const Args& a, int gw, int NGW, int lane_) {
;     ...
;         const int m0 = ch * 8, s0 = m0 % SEQ;
;         float pm2[8], pm1[8];
;         if (s0 >= 2) { unpack8(*(const u32x4*)(PROJ + (size_t)(m0 - 1) * PP + C_PR + c0), pm1); unpack8(*(const u32x4*)(PROJ + (size_t)(m0 - 2) * PP + C_PR + c0), pm2); }
;         else {
; #pragma unroll
;             for (int e = 0; e < 8; ++e) { pm1[e] = 0.f; pm2[e] = 0.f; }
;         }
;         Tok6 cur, nxt; p6_load(cur, PROJ, O, m0, c0);
.LBB0_554:
	s_bfe_i32 s5, s26, 0x1001c
	s_lshl_b32 s4, s26, 3
	s_lshr_b32 s5, s5, 19
	s_add_i32 s5, s4, s5
	s_and_b32 s5, s5, 0xffffe000
	s_sub_i32 s5, s4, s5
	s_cmp_lt_i32 s5, 2
	s_cbranch_scc1 .LBB0_556
	s_ashr_i32 s5, s4, 31
	s_lshl_b64 s[6:7], s[4:5], 12
	v_lshl_add_u64 v[60:61], v[74:75], 0, s[6:7]
	global_load_dwordx4 v[56:59], v[60:61], off offset:-1024
	v_add_co_u32_e32 v60, vcc, 0xfffff000, v60
	s_nop 1
	v_addc_co_u32_e32 v61, vcc, -1, v61, vcc
	global_load_dwordx4 v[60:63], v[60:61], off offset:-1024
	s_waitcnt vmcnt(1)
	v_lshlrev_b32_e32 v82, 16, v56
	v_and_b32_e32 v83, 0xffff0000, v56
	v_lshlrev_b32_e32 v84, 16, v57
	v_and_b32_e32 v85, 0xffff0000, v57
	v_lshlrev_b32_e32 v86, 16, v58
	v_and_b32_e32 v87, 0xffff0000, v58
	v_lshlrev_b32_e32 v88, 16, v59
	v_and_b32_e32 v89, 0xffff0000, v59
	s_waitcnt vmcnt(0)
	v_lshlrev_b32_e32 v90, 16, v60
	v_and_b32_e32 v91, 0xffff0000, v60
	v_lshlrev_b32_e32 v92, 16, v61
	v_and_b32_e32 v93, 0xffff0000, v61
	v_lshlrev_b32_e32 v94, 16, v62
	v_and_b32_e32 v95, 0xffff0000, v62
	v_lshlrev_b32_e32 v96, 16, v63
	v_and_b32_e32 v97, 0xffff0000, v63
	s_branch .LBB0_557
